# inproj: P column tiles 8-9 (F columns read by feat_b) stored with default policy, all other tiles nt
# speedup vs baseline: 1.0021x; 1.0021x over previous
; DI u32x2 pack4(f32x4 v) { u32x2 r = {cvtpk(v[0], v[1]), cvtpk(v[2], v[3])}; return r; }
; template <class Epi>
; DI void gemm256(const bf16_t* __restrict__ A, int lda, const bf16_t* __restrict__ Bt, int ldb, int K, char* lds, Epi epi) {
;     ...
;   float* ct = (float*)lds;
; #pragma unroll
;   for (int ai = 0; ai < 2; ++ai) {
;     __syncthreads();
; #pragma unroll
;     for (int bj = 0; bj < 2; ++bj)
; #pragma unroll
;       for (int m = 0; m < 4; ++m)
; #pragma unroll
;         for (int n = 0; n < 2; ++n)
; #pragma unroll
;           for (int j = 0; j < 4; ++j) ct[(wr * 64 + m * 16 + fq * 4 + j) * 260 + bj * 128 + wc * 32 + n * 16 + fr] = acc[ai][bj][m][n][j];
;     __syncthreads();
; #pragma unroll 2
;     for (int it = 0; it < 16; ++it) {
;       const int idx = it * NTHR + tid; const int row = idx >> 6, c4 = (idx & 63) * 4;
;       f32x4 v = *(const f32x4*)(ct + row * 260 + c4);
;       epi(ai * 128 + row, c4, v);
;     }
; DI void phase_inproj(KP p, int l, char* lds) {
;     ...
;       gemm256(hx + (size_t)m0 * 1024, 1024, wt + (size_t)n0 * 1024, 1024, 1024, lds, [&](int m, int n, f32x4 v) {
;         __builtin_nontemporal_store(pack4(v), (u32x2*)(P + (size_t)(m0 + m) * NIN + n0 + n));
;       });
.LBB0_321:
	s_or_b64 exec, exec, s[18:19]
	v_lshlrev_b32_e32 v0, 6, v141
	v_lshl_or_b32 v0, v144, 2, v0
	v_lshl_add_u32 v131, v142, 7, 0
	v_lshlrev_b32_e32 v132, 2, v145
	v_mul_lo_u32 v0, v0, s9
	v_add3_u32 v131, v131, v132, v0
	s_waitcnt vmcnt(0)
	s_barrier
	ds_write2_b32 v131, v114, v126 offset1:16
	v_add_u32_e32 v114, 0x400, v131
	ds_write2_b32 v114, v115, v127 offset0:4 offset1:20
	v_add_u32_e32 v115, 0x800, v131
	ds_write2_b32 v115, v116, v128 offset0:8 offset1:24
	v_add_u32_e32 v116, 0xc00, v131
	ds_write2_b32 v116, v117, v129 offset0:12 offset1:28
	v_add_u32_e32 v117, 0x4000, v131
	ds_write2_b32 v117, v82, v94 offset0:64 offset1:80
	v_add_u32_e32 v82, 0x4400, v131
	ds_write2_b32 v82, v83, v95 offset0:68 offset1:84
	v_add_u32_e32 v83, 0x4800, v131
	ds_write2_b32 v83, v84, v96 offset0:72 offset1:88
	v_add_u32_e32 v84, 0x4c00, v131
	ds_write2_b32 v84, v85, v97 offset0:76 offset1:92
	v_add_u32_e32 v85, 0x8000, v131
	ds_write2_b32 v85, v74, v78 offset0:128 offset1:144
	v_add_u32_e32 v74, 0x8400, v131
	ds_write2_b32 v74, v75, v79 offset0:132 offset1:148
	v_add_u32_e32 v75, 0x8800, v131
	ds_write2_b32 v75, v76, v80 offset0:136 offset1:152
	v_add_u32_e32 v76, 0x8c00, v131
	ds_write2_b32 v76, v77, v81 offset0:140 offset1:156
	v_add_u32_e32 v77, 0xc000, v131
	ds_write2_b32 v77, v66, v70 offset0:192 offset1:208
	v_add_u32_e32 v70, 0xc400, v131
	s_lshl_b64 s[18:19], s[2:3], 1
	v_and_b32_e32 v133, 0xfc, v143
	ds_write2_b32 v70, v67, v71 offset0:196 offset1:212
	v_add_u32_e32 v71, 0xc800, v131
	s_add_u32 s18, s42, s18
	ds_write2_b32 v71, v68, v72 offset0:200 offset1:216
	v_add_u32_e32 v68, 0xcc00, v131
	s_addc_u32 s19, s43, s19
	v_lshlrev_b32_e32 v0, 1, v133
	v_lshl_add_u32 v130, v133, 2, 0
	ds_write2_b32 v68, v69, v73 offset0:204 offset1:220
	ds_write2_b32 v131, v98, v118 offset0:128 offset1:144
	ds_write2_b32 v114, v99, v119 offset0:132 offset1:148
	ds_write2_b32 v115, v100, v120 offset0:136 offset1:152
	ds_write2_b32 v116, v101, v121 offset0:140 offset1:156
	ds_write2_b32 v117, v102, v122 offset0:192 offset1:208
	ds_write2_b32 v82, v103, v123 offset0:196 offset1:212
	ds_write2_b32 v83, v104, v124 offset0:200 offset1:216
	ds_write2_b32 v84, v105, v125 offset0:204 offset1:220
	ds_write2_b32 v74, v90, v110 offset1:16
	ds_write2_b32 v75, v91, v111 offset0:4 offset1:20
	ds_write2_b32 v76, v92, v112 offset0:8 offset1:24
	v_add_u32_e32 v69, 0x9000, v131
	v_add_u32_e32 v72, 0xd000, v131
	v_lshl_add_u64 v[66:67], s[18:19], 0, v[0:1]
	s_mov_b32 s2, 0
	ds_write2_b32 v69, v93, v113 offset0:12 offset1:28
	ds_write2_b32 v70, v86, v106 offset0:64 offset1:80
	ds_write2_b32 v71, v87, v107 offset0:68 offset1:84
	ds_write2_b32 v68, v88, v108 offset0:72 offset1:88
	ds_write2_b32 v72, v89, v109 offset0:76 offset1:92
	s_waitcnt lgkmcnt(0)
	s_barrier
	v_and_b32_e32 v141, 31, v140
	v_lshrrev_b32_e32 v142, 5, v140
	v_lshlrev_b32_e32 v143, 4, v141
	v_mad_u32_u24 v143, v142, s11, v143
	v_lshlrev_b32_e32 v141, 5, v141
	v_mad_u32_u24 v141, v142, s9, v141
	v_add_u32_e32 v142, 0x10400, v141
	s_mul_i32 s20, s4, s11
	s_add_u32 s20, s18, s20
	s_addc_u32 s21, s19, 0
	ds_read_b128 v[144:147], v141 offset:0
	ds_read_b128 v[148:151], v141 offset:16
	ds_read_b128 v[152:155], v141 offset:16640
	ds_read_b128 v[156:159], v141 offset:16656
	ds_read_b128 v[160:163], v141 offset:33280
	ds_read_b128 v[164:167], v141 offset:33296
	ds_read_b128 v[168:171], v141 offset:49920
	ds_read_b128 v[172:175], v141 offset:49936
	s_waitcnt lgkmcnt(6)
	v_cvt_pk_bf16_f32 v144, v144, v145
	v_cvt_pk_bf16_f32 v145, v146, v147
	v_cvt_pk_bf16_f32 v146, v148, v149
	v_cvt_pk_bf16_f32 v147, v150, v151
	s_add_u32 s46, s20, 0x0
	s_addc_u32 s47, s21, 0
	s_cmpk_gt_u32 s57, 0x8f
	s_cbranch_scc1 .Lpd_0
	global_store_dwordx4 v143, v[144:147], s[46:47] nt
	s_branch .Lpe_0
.Lpd_0:
	global_store_dwordx4 v143, v[144:147], s[46:47]
.Lpe_0:
	s_waitcnt lgkmcnt(4)
	v_cvt_pk_bf16_f32 v152, v152, v153
	v_cvt_pk_bf16_f32 v153, v154, v155
	v_cvt_pk_bf16_f32 v154, v156, v157
	v_cvt_pk_bf16_f32 v155, v158, v159
	s_add_u32 s46, s20, 0x14c00
	s_addc_u32 s47, s21, 0
	s_cmpk_gt_u32 s57, 0x8f
	s_cbranch_scc1 .Lpd_1
	global_store_dwordx4 v143, v[152:155], s[46:47] nt
	s_branch .Lpe_1
.Lpd_1:
	global_store_dwordx4 v143, v[152:155], s[46:47]
.Lpe_1:
	s_waitcnt lgkmcnt(2)
	v_cvt_pk_bf16_f32 v160, v160, v161
	v_cvt_pk_bf16_f32 v161, v162, v163
	v_cvt_pk_bf16_f32 v162, v164, v165
	v_cvt_pk_bf16_f32 v163, v166, v167
	s_add_u32 s46, s20, 0x29800
	s_addc_u32 s47, s21, 0
	s_cmpk_gt_u32 s57, 0x8f
	s_cbranch_scc1 .Lpd_2
	global_store_dwordx4 v143, v[160:163], s[46:47] nt
	s_branch .Lpe_2
.Lpd_2:
	global_store_dwordx4 v143, v[160:163], s[46:47]
.Lpe_2:
	s_waitcnt lgkmcnt(0)
	v_cvt_pk_bf16_f32 v168, v168, v169
	v_cvt_pk_bf16_f32 v169, v170, v171
	v_cvt_pk_bf16_f32 v170, v172, v173
	v_cvt_pk_bf16_f32 v171, v174, v175
	s_add_u32 s46, s20, 0x3e400
	s_addc_u32 s47, s21, 0
	s_cmpk_gt_u32 s57, 0x8f
	s_cbranch_scc1 .Lpd_3
	global_store_dwordx4 v143, v[168:171], s[46:47] nt
	s_branch .Lpe_3
.Lpd_3:
	global_store_dwordx4 v143, v[168:171], s[46:47]
.Lpe_3:
	ds_read_b128 v[144:147], v142 offset:0
	ds_read_b128 v[148:151], v142 offset:16
	ds_read_b128 v[152:155], v142 offset:16640
	ds_read_b128 v[156:159], v142 offset:16656
	ds_read_b128 v[160:163], v142 offset:33280
	ds_read_b128 v[164:167], v142 offset:33296
	ds_read_b128 v[168:171], v142 offset:49920
	ds_read_b128 v[172:175], v142 offset:49936
	s_waitcnt lgkmcnt(6)
	v_cvt_pk_bf16_f32 v144, v144, v145
	v_cvt_pk_bf16_f32 v145, v146, v147
	v_cvt_pk_bf16_f32 v146, v148, v149
	v_cvt_pk_bf16_f32 v147, v150, v151
	s_add_u32 s46, s20, 0x53000
	s_addc_u32 s47, s21, 0
	s_cmpk_gt_u32 s57, 0x8f
	s_cbranch_scc1 .Lpd_4
	global_store_dwordx4 v143, v[144:147], s[46:47] nt
	s_branch .Lpe_4

; DI u32x2 pack4(f32x4 v) { u32x2 r = {cvtpk(v[0], v[1]), cvtpk(v[2], v[3])}; return r; }
; template <class Epi>
; DI void gemm256(const bf16_t* __restrict__ A, int lda, const bf16_t* __restrict__ Bt, int ldb, int K, char* lds, Epi epi) {
;     ...
;     for (int it = 0; it < 16; ++it) {
;       const int idx = it * NTHR + tid; const int row = idx >> 6, c4 = (idx & 63) * 4;
;       f32x4 v = *(const f32x4*)(ct + row * 260 + c4);
;       epi(ai * 128 + row, c4, v);
;     }
; DI void phase_inproj(KP p, int l, char* lds) {
;     ...
;       gemm256(hx + (size_t)m0 * 1024, 1024, wt + (size_t)n0 * 1024, 1024, 1024, lds, [&](int m, int n, f32x4 v) {
;         __builtin_nontemporal_store(pack4(v), (u32x2*)(P + (size_t)(m0 + m) * NIN + n0 + n));
;       });
.Lpe_4:
	s_waitcnt lgkmcnt(4)
	v_cvt_pk_bf16_f32 v152, v152, v153
	v_cvt_pk_bf16_f32 v153, v154, v155
	v_cvt_pk_bf16_f32 v154, v156, v157
	v_cvt_pk_bf16_f32 v155, v158, v159
	s_add_u32 s46, s20, 0x67c00
	s_addc_u32 s47, s21, 0
	s_cmpk_gt_u32 s57, 0x8f
	s_cbranch_scc1 .Lpd_5
	global_store_dwordx4 v143, v[152:155], s[46:47] nt
	s_branch .Lpe_5

; DI u32x2 pack4(f32x4 v) { u32x2 r = {cvtpk(v[0], v[1]), cvtpk(v[2], v[3])}; return r; }
; template <class Epi>
; DI void gemm256(const bf16_t* __restrict__ A, int lda, const bf16_t* __restrict__ Bt, int ldb, int K, char* lds, Epi epi) {
;     ...
;     for (int it = 0; it < 16; ++it) {
;       const int idx = it * NTHR + tid; const int row = idx >> 6, c4 = (idx & 63) * 4;
;       f32x4 v = *(const f32x4*)(ct + row * 260 + c4);
;       epi(ai * 128 + row, c4, v);
;     }
; DI void phase_inproj(KP p, int l, char* lds) {
;     ...
;       gemm256(hx + (size_t)m0 * 1024, 1024, wt + (size_t)n0 * 1024, 1024, 1024, lds, [&](int m, int n, f32x4 v) {
;         __builtin_nontemporal_store(pack4(v), (u32x2*)(P + (size_t)(m0 + m) * NIN + n0 + n));
;       });
.Lpe_5:
	s_waitcnt lgkmcnt(2)
	v_cvt_pk_bf16_f32 v160, v160, v161
	v_cvt_pk_bf16_f32 v161, v162, v163
	v_cvt_pk_bf16_f32 v162, v164, v165
	v_cvt_pk_bf16_f32 v163, v166, v167
	s_add_u32 s46, s20, 0x7c800
	s_addc_u32 s47, s21, 0
	s_cmpk_gt_u32 s57, 0x8f
	s_cbranch_scc1 .Lpd_6
	global_store_dwordx4 v143, v[160:163], s[46:47] nt
	s_branch .Lpe_6

; DI u32x2 pack4(f32x4 v) { u32x2 r = {cvtpk(v[0], v[1]), cvtpk(v[2], v[3])}; return r; }
; template <class Epi>
; DI void gemm256(const bf16_t* __restrict__ A, int lda, const bf16_t* __restrict__ Bt, int ldb, int K, char* lds, Epi epi) {
;     ...
;     for (int it = 0; it < 16; ++it) {
;       const int idx = it * NTHR + tid; const int row = idx >> 6, c4 = (idx & 63) * 4;
;       f32x4 v = *(const f32x4*)(ct + row * 260 + c4);
;       epi(ai * 128 + row, c4, v);
;     }
; DI void phase_inproj(KP p, int l, char* lds) {
;     ...
;       gemm256(hx + (size_t)m0 * 1024, 1024, wt + (size_t)n0 * 1024, 1024, 1024, lds, [&](int m, int n, f32x4 v) {
;         __builtin_nontemporal_store(pack4(v), (u32x2*)(P + (size_t)(m0 + m) * NIN + n0 + n));
;       });
.Lpe_6:
	s_waitcnt lgkmcnt(0)
	v_cvt_pk_bf16_f32 v168, v168, v169
	v_cvt_pk_bf16_f32 v169, v170, v171
	v_cvt_pk_bf16_f32 v170, v172, v173
	v_cvt_pk_bf16_f32 v171, v174, v175
	s_add_u32 s46, s20, 0x91400
	s_addc_u32 s47, s21, 0
	s_cmpk_gt_u32 s57, 0x8f
	s_cbranch_scc1 .Lpd_7
	global_store_dwordx4 v143, v[168:171], s[46:47] nt
	s_branch .Lpe_7

; DI u32x2 pack4(f32x4 v) { u32x2 r = {cvtpk(v[0], v[1]), cvtpk(v[2], v[3])}; return r; }
; template <class Epi>
; DI void gemm256(const bf16_t* __restrict__ A, int lda, const bf16_t* __restrict__ Bt, int ldb, int K, char* lds, Epi epi) {
;     ...
; #pragma unroll
;   for (int ai = 0; ai < 2; ++ai) {
;     __syncthreads();
; #pragma unroll
;     for (int bj = 0; bj < 2; ++bj)
; #pragma unroll
;       for (int m = 0; m < 4; ++m)
; #pragma unroll
;         for (int n = 0; n < 2; ++n)
; #pragma unroll
;           for (int j = 0; j < 4; ++j) ct[(wr * 64 + m * 16 + fq * 4 + j) * 260 + bj * 128 + wc * 32 + n * 16 + fr] = acc[ai][bj][m][n][j];
;     __syncthreads();
; #pragma unroll 2
;     for (int it = 0; it < 16; ++it) {
;       const int idx = it * NTHR + tid; const int row = idx >> 6, c4 = (idx & 63) * 4;
;       f32x4 v = *(const f32x4*)(ct + row * 260 + c4);
;       epi(ai * 128 + row, c4, v);
;     }
; DI void phase_inproj(KP p, int l, char* lds) {
;     ...
;       gemm256(hx + (size_t)m0 * 1024, 1024, wt + (size_t)n0 * 1024, 1024, 1024, lds, [&](int m, int n, f32x4 v) {
;         __builtin_nontemporal_store(pack4(v), (u32x2*)(P + (size_t)(m0 + m) * NIN + n0 + n));
;       });
.Lpe_7:
	s_or_b32 s2, s4, 0x80
	s_mov_b32 s4, 0
	s_waitcnt lgkmcnt(0)
	s_barrier
	ds_write2_b32 v131, v2, v18 offset1:16
	ds_write2_b32 v114, v3, v19 offset0:4 offset1:20
	ds_write2_b32 v115, v4, v20 offset0:8 offset1:24
	ds_write2_b32 v116, v5, v21 offset0:12 offset1:28
	ds_write2_b32 v117, v6, v22 offset0:64 offset1:80
	ds_write2_b32 v82, v7, v23 offset0:68 offset1:84
	ds_write2_b32 v83, v8, v24 offset0:72 offset1:88
	ds_write2_b32 v84, v9, v25 offset0:76 offset1:92
	ds_write2_b32 v85, v10, v26 offset0:128 offset1:144
	ds_write2_b32 v74, v11, v27 offset0:132 offset1:148
	ds_write2_b32 v75, v12, v28 offset0:136 offset1:152
	ds_write2_b32 v76, v13, v29 offset0:140 offset1:156
	ds_write2_b32 v77, v14, v30 offset0:192 offset1:208
	ds_write2_b32 v70, v15, v31 offset0:196 offset1:212
	ds_write2_b32 v71, v16, v32 offset0:200 offset1:216
	ds_write2_b32 v68, v17, v33 offset0:204 offset1:220
	ds_write2_b32 v131, v34, v50 offset0:128 offset1:144
	ds_write2_b32 v114, v35, v51 offset0:132 offset1:148
	ds_write2_b32 v115, v36, v52 offset0:136 offset1:152
	ds_write2_b32 v116, v37, v53 offset0:140 offset1:156
	ds_write2_b32 v117, v38, v54 offset0:192 offset1:208
	ds_write2_b32 v82, v39, v55 offset0:196 offset1:212
	ds_write2_b32 v83, v40, v56 offset0:200 offset1:216
	ds_write2_b32 v84, v41, v57 offset0:204 offset1:220
	ds_write2_b32 v74, v42, v58 offset1:16
	ds_write2_b32 v75, v43, v59 offset0:4 offset1:20
	ds_write2_b32 v76, v44, v60 offset0:8 offset1:24
	ds_write2_b32 v69, v45, v61 offset0:12 offset1:28
	ds_write2_b32 v70, v46, v62 offset0:64 offset1:80
	ds_write2_b32 v71, v47, v63 offset0:68 offset1:84
	ds_write2_b32 v68, v48, v64 offset0:72 offset1:88
	ds_write2_b32 v72, v49, v65 offset0:76 offset1:92
	s_waitcnt lgkmcnt(0)
	s_barrier
	s_mul_i32 s20, s2, s11
	s_add_u32 s20, s18, s20
	s_addc_u32 s21, s19, 0
	ds_read_b128 v[144:147], v141 offset:0
	ds_read_b128 v[148:151], v141 offset:16
	ds_read_b128 v[152:155], v141 offset:16640
	ds_read_b128 v[156:159], v141 offset:16656
	ds_read_b128 v[160:163], v141 offset:33280
	ds_read_b128 v[164:167], v141 offset:33296
	ds_read_b128 v[168:171], v141 offset:49920
	ds_read_b128 v[172:175], v141 offset:49936
	s_waitcnt lgkmcnt(6)
	v_cvt_pk_bf16_f32 v144, v144, v145
	v_cvt_pk_bf16_f32 v145, v146, v147
	v_cvt_pk_bf16_f32 v146, v148, v149
	v_cvt_pk_bf16_f32 v147, v150, v151
	s_add_u32 s46, s20, 0x0
	s_addc_u32 s47, s21, 0
	s_cmpk_gt_u32 s57, 0x8f
	s_cbranch_scc1 .Lpd_8
	global_store_dwordx4 v143, v[144:147], s[46:47] nt
	s_branch .Lpe_8

; DI u32x2 pack4(f32x4 v) { u32x2 r = {cvtpk(v[0], v[1]), cvtpk(v[2], v[3])}; return r; }
; DI void phase_inproj(KP p, int l, char* lds) {
;     ...
;   const int nfull = NBIG % nlb, nfree = (nfull == 0) ? nlb : nlb - nfull;
;   for (int sp = (nfull == 0) ? lb : lb - nfull; sp >= 0 && sp < 18; sp += nfree) {
;     {
;       const int mt = 36 * xcd + 2 * sp + hb;
;       if (l == 1 && (mt % 18) >= 16) continue;
;       const int m0 = mt * 128;
;       gemm_tile(hx + (size_t)m0 * 1024, 1024, wt + (size_t)2560 * 1024, 1024, 1024, lds, [&](int m, int n, f32x4 v) {
;         if (2560 + n < NIN) __builtin_nontemporal_store(pack4(v), (u32x2*)(P + (size_t)(m0 + m) * NIN + 2560 + n));
.Lpe_15:
	s_waitcnt lgkmcnt(0)
	s_barrier
	s_branch .LBB0_304
.LBB0_326:
	v_readlane_b32 s4, v254, 35
	v_readlane_b32 s5, v254, 36
	s_andn2_b64 vcc, exec, s[4:5]
	s_cbranch_vccnz .LBB0_339
	s_ashr_i32 s18, s56, 8
	v_readlane_b32 s2, v254, 55
	v_readlane_b32 s4, v253, 2
	s_add_i32 s2, s18, s2
	s_add_i32 s4, s4, -8
	v_readlane_b32 s5, v253, 3
	s_cmp_lt_u32 s4, 7
	s_cselect_b64 s[4:5], -1, 0
	s_add_u32 s46, s54, 0x500000
	s_addc_u32 s47, s55, 0
	s_add_u32 s48, s36, s53
	v_readlane_b32 s19, v254, 41
	s_addc_u32 s49, s37, s52
	s_add_i32 s19, s19, s18
	s_lshl_b32 s54, s19, 7
	s_lshl_b32 s18, s18, 7
	v_readlane_b32 s19, v254, 44
	s_add_i32 s20, s19, s18
	v_readlane_b32 s21, v254, 34
	s_waitcnt vmcnt(0)
	s_branch .LBB0_330
